# moba block-selection loop: all eight LDS reads of a block row issued at the loop top into distinct registers, counted lgkmcnt waits
# baseline (speedup 1.0000x reference)
.LBB0_589:
	ds_read_b128 v[44:47], v1
	ds_read_b128 v[48:51], v1 offset:16
	ds_read_b128 v[52:55], v1 offset:64
	ds_read_b128 v[56:59], v1 offset:80
	ds_read_b128 v[60:63], v1 offset:128
	ds_read_b128 v[218:221], v1 offset:144
	ds_read_b128 v[222:225], v1 offset:192
	ds_read_b128 v[226:229], v1 offset:208
	s_waitcnt lgkmcnt(7)
	v_fma_f32 v43, v44, v15, 0
	v_fmac_f32_e32 v43, v45, v16
	v_fmac_f32_e32 v43, v46, v17
	v_fmac_f32_e32 v43, v47, v18
	s_waitcnt lgkmcnt(6)
	v_fmac_f32_e32 v43, v48, v19
	v_fmac_f32_e32 v43, v49, v20
	v_fmac_f32_e32 v43, v50, v21
	v_fmac_f32_e32 v43, v51, v22
	s_waitcnt lgkmcnt(5)
	v_fmac_f32_e32 v43, v52, v23
	v_fmac_f32_e32 v43, v53, v24
	v_fmac_f32_e32 v43, v54, v25
	v_fmac_f32_e32 v43, v55, v26
	s_waitcnt lgkmcnt(4)
	v_fmac_f32_e32 v43, v56, v27
	v_fmac_f32_e32 v43, v57, v28
	v_fmac_f32_e32 v43, v58, v29
	v_fmac_f32_e32 v43, v59, v30
	s_waitcnt lgkmcnt(3)
	v_fmac_f32_e32 v43, v60, v31
	v_fmac_f32_e32 v43, v61, v32
	v_fmac_f32_e32 v43, v62, v35
	v_fmac_f32_e32 v43, v63, v37
	s_waitcnt lgkmcnt(2)
	v_pk_mul_f32 v[44:45], v[218:219], v[2:3]
	s_waitcnt lgkmcnt(1)
	v_pk_mul_f32 v[48:49], v[222:223], v[6:7]
	v_add_f32_e32 v43, v43, v44
	v_add_f32_e32 v43, v45, v43
	v_pk_mul_f32 v[44:45], v[220:221], v[4:5]
	s_nop 0
	v_add_f32_e32 v43, v43, v44
	v_add_f32_e32 v43, v45, v43
	v_add_f32_e32 v43, v43, v48
	v_add_f32_e32 v43, v49, v43
	v_pk_mul_f32 v[48:49], v[224:225], v[8:9]
	s_waitcnt lgkmcnt(0)
	v_pk_mul_f32 v[44:45], v[226:227], v[10:11]
	v_add_f32_e32 v43, v43, v48
	v_add_f32_e32 v43, v49, v43
	v_add_f32_e32 v43, v43, v44
	v_add_f32_e32 v43, v45, v43
	v_pk_mul_f32 v[44:45], v[228:229], v[12:13]
	v_mov_b32_e32 v46, v39
	v_add_f32_e32 v43, v43, v44
	v_add_f32_e32 v43, v45, v43
	v_mov_b32_e32 v44, v43
	v_mov_b32_e32 v45, s11
	s_nop 1
	v_permlane32_swap_b32_e32 v44, v43
	v_add_f32_e32 v44, v43, v44
	v_cmp_ngt_f32_e32 vcc, v44, v39
	v_mov_b32_e32 v43, v36
	s_and_saveexec_b64 s[4:5], vcc
	s_cbranch_execz .LBB0_595
	v_cmp_ngt_f32_e32 vcc, v44, v40
	v_mov_b32_e32 v43, s11
	s_and_saveexec_b64 s[6:7], vcc
	s_cbranch_execz .LBB0_594
	v_cmp_gt_f32_e32 vcc, v44, v42
	s_and_saveexec_b64 s[8:9], vcc
	v_mov_b32_e32 v38, s11
	v_mov_b32_e32 v42, v44
	s_or_b64 exec, exec, s[8:9]
	v_mov_b32_e32 v44, v40
	v_mov_b32_e32 v40, v42
	v_mov_b32_e32 v43, v41
	v_mov_b32_e32 v41, v38
